# in-projection 0 start: qk-gain table load issued with the first table batch; in-projection 1 start: both counter polls loaded together
# baseline (speedup 1.0000x reference)
.LBB0_301:
.LBB0_302:
	s_xor_b64 s[4:5], s[4:5], -1
	v_writelane_b32 v252, s4, 3
	s_cmp_lt_i32 s20, 3
	s_nop 0
	v_writelane_b32 v252, s5, 4
	s_cselect_b64 s[4:5], -1, 0
	s_cmp_gt_i32 s21, 2
	s_cselect_b64 s[6:7], -1, 0
	s_and_b64 s[4:5], s[4:5], s[6:7]
	s_andn2_b64 vcc, exec, s[4:5]
	s_cbranch_vccnz .LBB0_640
	s_mov_b64 s[4:5], s[0:1]
	v_mov_b32_e32 v0, v244
	s_load_dwordx2 s[6:7], s[4:5], 0xa8
	s_load_dwordx2 s[98:99], s[4:5], 0x48
	v_add_u32_e32 v0, s76, v0
	s_waitcnt vmcnt(0)
	v_ashrrev_i32_e32 v1, 31, v0
	s_mov_b64 s[4:5], s[0:1]
	s_waitcnt lgkmcnt(0)
	v_lshl_add_u64 v[2:3], v[0:1], 2, s[6:7]
	v_add_co_u32_e32 v4, vcc, 0x136000, v2
	s_movk_i32 s3, 0x80
	s_nop 0
	v_addc_co_u32_e32 v5, vcc, 0, v3, vcc
	v_add_co_u32_e32 v6, vcc, 0x137000, v2
	s_nop 1
	v_addc_co_u32_e32 v7, vcc, 0, v3, vcc
	v_add_co_u32_e32 v8, vcc, 0x138000, v2
	s_nop 1
	v_addc_co_u32_e32 v9, vcc, 0, v3, vcc
	global_load_dword v10, v[4:5], off
	global_load_dword v11, v[4:5], off offset:2048
	global_load_dword v12, v[6:7], off
	global_load_dword v13, v[6:7], off offset:2048
	global_load_dword v1, v[8:9], off
	global_load_dword v2, v[8:9], off offset:2048
	v_and_b32_e32 v14, 0x7f, v0
	v_lshlrev_b32_e32 v14, 2, v14
	global_load_dword v14, v14, s[98:99]
	v_lshl_add_u32 v3, v0, 2, 0
	v_add_u32_e32 v3, 0x20000, v3
	v_cmp_gt_i32_e32 vcc, s3, v0
	s_waitcnt vmcnt(5)
	ds_write2st64_b32 v3, v10, v11 offset1:8
	s_waitcnt vmcnt(3)
	ds_write2st64_b32 v3, v12, v13 offset0:16 offset1:24
	s_and_saveexec_b64 s[6:7], vcc
	s_cbranch_execz .LBB0_305
	s_waitcnt vmcnt(0)
	ds_write_b32 v3, v14 offset:8192

.LBB0_922:
	global_load_dword v2, v1, s[6:7] sc1
	global_load_dword v3, v1, s[4:5] sc1
	s_waitcnt vmcnt(0)
	v_cmp_gt_u32_e32 vcc, 48, v2
	s_cbranch_vccnz .LBB0_924
	s_cmp_lg_u32 s3, 0
	s_cselect_b64 s[8:9], -1, 0
	v_cmp_gt_u32_e32 vcc, s14, v3
	s_and_b64 s[8:9], vcc, s[8:9]
	s_cbranch_execz .LBB0_925
	s_branch .LBB0_926
